# startup placement check (group_mode): the 128 census words are read 64 at a time instead of eight dependent batches of 16 (prologue de-serialisation)
# baseline (speedup 1.0000x reference)
.LBB0_92:
	s_add_u32 s6, s46, 0x0
	s_addc_u32 s7, s47, 0
	global_load_dword v3, v0, s[6:7] sc1
	global_load_dword v4, v0, s[6:7] offset:256 sc1
	global_load_dword v5, v0, s[6:7] offset:512 sc1
	global_load_dword v6, v0, s[6:7] offset:768 sc1
	global_load_dword v7, v0, s[6:7] offset:1024 sc1
	global_load_dword v8, v0, s[6:7] offset:1280 sc1
	global_load_dword v9, v0, s[6:7] offset:1536 sc1
	global_load_dword v10, v0, s[6:7] offset:1792 sc1
	global_load_dword v11, v0, s[6:7] offset:2048 sc1
	global_load_dword v12, v0, s[6:7] offset:2304 sc1
	global_load_dword v13, v0, s[6:7] offset:2560 sc1
	global_load_dword v14, v0, s[6:7] offset:2816 sc1
	global_load_dword v15, v0, s[6:7] offset:3072 sc1
	global_load_dword v16, v0, s[6:7] offset:3328 sc1
	global_load_dword v17, v0, s[6:7] offset:3584 sc1
	global_load_dword v18, v0, s[6:7] offset:3840 sc1
	s_add_u32 s6, s46, 0x1000
	s_addc_u32 s7, s47, 0
	global_load_dword v19, v0, s[6:7] sc1
	global_load_dword v20, v0, s[6:7] offset:256 sc1
	global_load_dword v21, v0, s[6:7] offset:512 sc1
	global_load_dword v22, v0, s[6:7] offset:768 sc1
	global_load_dword v23, v0, s[6:7] offset:1024 sc1
	global_load_dword v24, v0, s[6:7] offset:1280 sc1
	global_load_dword v25, v0, s[6:7] offset:1536 sc1
	global_load_dword v26, v0, s[6:7] offset:1792 sc1
	global_load_dword v27, v0, s[6:7] offset:2048 sc1
	global_load_dword v28, v0, s[6:7] offset:2304 sc1
	global_load_dword v29, v0, s[6:7] offset:2560 sc1
	global_load_dword v30, v0, s[6:7] offset:2816 sc1
	global_load_dword v31, v0, s[6:7] offset:3072 sc1
	global_load_dword v32, v0, s[6:7] offset:3328 sc1
	global_load_dword v33, v0, s[6:7] offset:3584 sc1
	global_load_dword v34, v0, s[6:7] offset:3840 sc1
	s_add_u32 s6, s46, 0x2000
	s_addc_u32 s7, s47, 0
	global_load_dword v35, v0, s[6:7] sc1
	global_load_dword v36, v0, s[6:7] offset:256 sc1
	global_load_dword v37, v0, s[6:7] offset:512 sc1
	global_load_dword v38, v0, s[6:7] offset:768 sc1
	global_load_dword v39, v0, s[6:7] offset:1024 sc1
	global_load_dword v40, v0, s[6:7] offset:1280 sc1
	global_load_dword v41, v0, s[6:7] offset:1536 sc1
	global_load_dword v42, v0, s[6:7] offset:1792 sc1
	global_load_dword v43, v0, s[6:7] offset:2048 sc1
	global_load_dword v44, v0, s[6:7] offset:2304 sc1
	global_load_dword v45, v0, s[6:7] offset:2560 sc1
	global_load_dword v46, v0, s[6:7] offset:2816 sc1
	global_load_dword v47, v0, s[6:7] offset:3072 sc1
	global_load_dword v48, v0, s[6:7] offset:3328 sc1
	global_load_dword v49, v0, s[6:7] offset:3584 sc1
	global_load_dword v50, v0, s[6:7] offset:3840 sc1
	s_add_u32 s6, s46, 0x3000
	s_addc_u32 s7, s47, 0
	global_load_dword v51, v0, s[6:7] sc1
	global_load_dword v52, v0, s[6:7] offset:256 sc1
	global_load_dword v53, v0, s[6:7] offset:512 sc1
	global_load_dword v54, v0, s[6:7] offset:768 sc1
	global_load_dword v55, v0, s[6:7] offset:1024 sc1
	global_load_dword v56, v0, s[6:7] offset:1280 sc1
	global_load_dword v57, v0, s[6:7] offset:1536 sc1
	global_load_dword v58, v0, s[6:7] offset:1792 sc1
	global_load_dword v59, v0, s[6:7] offset:2048 sc1
	global_load_dword v60, v0, s[6:7] offset:2304 sc1
	global_load_dword v61, v0, s[6:7] offset:2560 sc1
	global_load_dword v62, v0, s[6:7] offset:2816 sc1
	global_load_dword v63, v0, s[6:7] offset:3072 sc1
	global_load_dword v64, v0, s[6:7] offset:3328 sc1
	global_load_dword v65, v0, s[6:7] offset:3584 sc1
	global_load_dword v66, v0, s[6:7] offset:3840 sc1
	s_waitcnt vmcnt(0)
	v_add_u32_e32 v2, v3, v2
	v_add_u32_e32 v2, v4, v2
	v_add_u32_e32 v2, v5, v2
	v_add_u32_e32 v2, v6, v2
	v_add_u32_e32 v2, v7, v2
	v_add_u32_e32 v2, v8, v2
	v_add_u32_e32 v2, v9, v2
	v_add_u32_e32 v2, v10, v2
	v_add_u32_e32 v2, v11, v2
	v_add_u32_e32 v2, v12, v2
	v_add_u32_e32 v2, v13, v2
	v_add_u32_e32 v2, v14, v2
	v_add_u32_e32 v2, v15, v2
	v_add_u32_e32 v2, v16, v2
	v_add_u32_e32 v2, v17, v2
	v_add_u32_e32 v2, v18, v2
	v_add_u32_e32 v2, v19, v2
	v_add_u32_e32 v2, v20, v2
	v_add_u32_e32 v2, v21, v2
	v_add_u32_e32 v2, v22, v2
	v_add_u32_e32 v2, v23, v2
	v_add_u32_e32 v2, v24, v2
	v_add_u32_e32 v2, v25, v2
	v_add_u32_e32 v2, v26, v2
	v_add_u32_e32 v2, v27, v2
	v_add_u32_e32 v2, v28, v2
	v_add_u32_e32 v2, v29, v2
	v_add_u32_e32 v2, v30, v2
	v_add_u32_e32 v2, v31, v2
	v_add_u32_e32 v2, v32, v2
	v_add_u32_e32 v2, v33, v2
	v_add_u32_e32 v2, v34, v2
	v_add_u32_e32 v2, v35, v2
	v_add_u32_e32 v2, v36, v2
	v_add_u32_e32 v2, v37, v2
	v_add_u32_e32 v2, v38, v2
	v_add_u32_e32 v2, v39, v2
	v_add_u32_e32 v2, v40, v2
	v_add_u32_e32 v2, v41, v2
	v_add_u32_e32 v2, v42, v2
	v_add_u32_e32 v2, v43, v2
	v_add_u32_e32 v2, v44, v2
	v_add_u32_e32 v2, v45, v2
	v_add_u32_e32 v2, v46, v2
	v_add_u32_e32 v2, v47, v2
	v_add_u32_e32 v2, v48, v2
	v_add_u32_e32 v2, v49, v2
	v_add_u32_e32 v2, v50, v2
	v_add_u32_e32 v2, v51, v2
	v_add_u32_e32 v2, v52, v2
	v_add_u32_e32 v2, v53, v2
	v_add_u32_e32 v2, v54, v2
	v_add_u32_e32 v2, v55, v2
	v_add_u32_e32 v2, v56, v2
	v_add_u32_e32 v2, v57, v2
	v_add_u32_e32 v2, v58, v2
	v_add_u32_e32 v2, v59, v2
	v_add_u32_e32 v2, v60, v2
	v_add_u32_e32 v2, v61, v2
	v_add_u32_e32 v2, v62, v2
	v_add_u32_e32 v2, v63, v2
	v_add_u32_e32 v2, v64, v2
	v_add_u32_e32 v2, v65, v2
	v_add_u32_e32 v2, v66, v2
	s_add_u32 s6, s46, 0x4000
	s_addc_u32 s7, s47, 0
	global_load_dword v3, v0, s[6:7] sc1
	global_load_dword v4, v0, s[6:7] offset:256 sc1
	global_load_dword v5, v0, s[6:7] offset:512 sc1
	global_load_dword v6, v0, s[6:7] offset:768 sc1
	global_load_dword v7, v0, s[6:7] offset:1024 sc1
	global_load_dword v8, v0, s[6:7] offset:1280 sc1
	global_load_dword v9, v0, s[6:7] offset:1536 sc1
	global_load_dword v10, v0, s[6:7] offset:1792 sc1
	global_load_dword v11, v0, s[6:7] offset:2048 sc1
	global_load_dword v12, v0, s[6:7] offset:2304 sc1
	global_load_dword v13, v0, s[6:7] offset:2560 sc1
	global_load_dword v14, v0, s[6:7] offset:2816 sc1
	global_load_dword v15, v0, s[6:7] offset:3072 sc1
	global_load_dword v16, v0, s[6:7] offset:3328 sc1
	global_load_dword v17, v0, s[6:7] offset:3584 sc1
	global_load_dword v18, v0, s[6:7] offset:3840 sc1
	s_add_u32 s6, s46, 0x5000
	s_addc_u32 s7, s47, 0
	global_load_dword v19, v0, s[6:7] sc1
	global_load_dword v20, v0, s[6:7] offset:256 sc1
	global_load_dword v21, v0, s[6:7] offset:512 sc1
	global_load_dword v22, v0, s[6:7] offset:768 sc1
	global_load_dword v23, v0, s[6:7] offset:1024 sc1
	global_load_dword v24, v0, s[6:7] offset:1280 sc1
	global_load_dword v25, v0, s[6:7] offset:1536 sc1
	global_load_dword v26, v0, s[6:7] offset:1792 sc1
	global_load_dword v27, v0, s[6:7] offset:2048 sc1
	global_load_dword v28, v0, s[6:7] offset:2304 sc1
	global_load_dword v29, v0, s[6:7] offset:2560 sc1
	global_load_dword v30, v0, s[6:7] offset:2816 sc1
	global_load_dword v31, v0, s[6:7] offset:3072 sc1
	global_load_dword v32, v0, s[6:7] offset:3328 sc1
	global_load_dword v33, v0, s[6:7] offset:3584 sc1
	global_load_dword v34, v0, s[6:7] offset:3840 sc1
	s_add_u32 s6, s46, 0x6000
	s_addc_u32 s7, s47, 0
	global_load_dword v35, v0, s[6:7] sc1
	global_load_dword v36, v0, s[6:7] offset:256 sc1
	global_load_dword v37, v0, s[6:7] offset:512 sc1
	global_load_dword v38, v0, s[6:7] offset:768 sc1
	global_load_dword v39, v0, s[6:7] offset:1024 sc1
	global_load_dword v40, v0, s[6:7] offset:1280 sc1
	global_load_dword v41, v0, s[6:7] offset:1536 sc1
	global_load_dword v42, v0, s[6:7] offset:1792 sc1
	global_load_dword v43, v0, s[6:7] offset:2048 sc1
	global_load_dword v44, v0, s[6:7] offset:2304 sc1
	global_load_dword v45, v0, s[6:7] offset:2560 sc1
	global_load_dword v46, v0, s[6:7] offset:2816 sc1
	global_load_dword v47, v0, s[6:7] offset:3072 sc1
	global_load_dword v48, v0, s[6:7] offset:3328 sc1
	global_load_dword v49, v0, s[6:7] offset:3584 sc1
	global_load_dword v50, v0, s[6:7] offset:3840 sc1
	s_add_u32 s6, s46, 0x7000
	s_addc_u32 s7, s47, 0
	global_load_dword v51, v0, s[6:7] sc1
	global_load_dword v52, v0, s[6:7] offset:256 sc1
	global_load_dword v53, v0, s[6:7] offset:512 sc1
	global_load_dword v54, v0, s[6:7] offset:768 sc1
	global_load_dword v55, v0, s[6:7] offset:1024 sc1
	global_load_dword v56, v0, s[6:7] offset:1280 sc1
	global_load_dword v57, v0, s[6:7] offset:1536 sc1
	global_load_dword v58, v0, s[6:7] offset:1792 sc1
	global_load_dword v59, v0, s[6:7] offset:2048 sc1
	global_load_dword v60, v0, s[6:7] offset:2304 sc1
	global_load_dword v61, v0, s[6:7] offset:2560 sc1
	global_load_dword v62, v0, s[6:7] offset:2816 sc1
	global_load_dword v63, v0, s[6:7] offset:3072 sc1
	global_load_dword v64, v0, s[6:7] offset:3328 sc1
	global_load_dword v65, v0, s[6:7] offset:3584 sc1
	global_load_dword v66, v0, s[6:7] offset:3840 sc1
	s_waitcnt vmcnt(0)
	v_add_u32_e32 v2, v3, v2
	v_add_u32_e32 v2, v4, v2
	v_add_u32_e32 v2, v5, v2
	v_add_u32_e32 v2, v6, v2
	v_add_u32_e32 v2, v7, v2
	v_add_u32_e32 v2, v8, v2
	v_add_u32_e32 v2, v9, v2
	v_add_u32_e32 v2, v10, v2
	v_add_u32_e32 v2, v11, v2
	v_add_u32_e32 v2, v12, v2
	v_add_u32_e32 v2, v13, v2
	v_add_u32_e32 v2, v14, v2
	v_add_u32_e32 v2, v15, v2
	v_add_u32_e32 v2, v16, v2
	v_add_u32_e32 v2, v17, v2
	v_add_u32_e32 v2, v18, v2
	v_add_u32_e32 v2, v19, v2
	v_add_u32_e32 v2, v20, v2
	v_add_u32_e32 v2, v21, v2
	v_add_u32_e32 v2, v22, v2
	v_add_u32_e32 v2, v23, v2
	v_add_u32_e32 v2, v24, v2
	v_add_u32_e32 v2, v25, v2
	v_add_u32_e32 v2, v26, v2
	v_add_u32_e32 v2, v27, v2
	v_add_u32_e32 v2, v28, v2
	v_add_u32_e32 v2, v29, v2
	v_add_u32_e32 v2, v30, v2
	v_add_u32_e32 v2, v31, v2
	v_add_u32_e32 v2, v32, v2
	v_add_u32_e32 v2, v33, v2
	v_add_u32_e32 v2, v34, v2
	v_add_u32_e32 v2, v35, v2
	v_add_u32_e32 v2, v36, v2
	v_add_u32_e32 v2, v37, v2
	v_add_u32_e32 v2, v38, v2
	v_add_u32_e32 v2, v39, v2
	v_add_u32_e32 v2, v40, v2
	v_add_u32_e32 v2, v41, v2
	v_add_u32_e32 v2, v42, v2
	v_add_u32_e32 v2, v43, v2
	v_add_u32_e32 v2, v44, v2
	v_add_u32_e32 v2, v45, v2
	v_add_u32_e32 v2, v46, v2
	v_add_u32_e32 v2, v47, v2
	v_add_u32_e32 v2, v48, v2
	v_add_u32_e32 v2, v49, v2
	v_add_u32_e32 v2, v50, v2
	v_add_u32_e32 v2, v51, v2
	v_add_u32_e32 v2, v52, v2
	v_add_u32_e32 v2, v53, v2
	v_add_u32_e32 v2, v54, v2
	v_add_u32_e32 v2, v55, v2
	v_add_u32_e32 v2, v56, v2
	v_add_u32_e32 v2, v57, v2
	v_add_u32_e32 v2, v58, v2
	v_add_u32_e32 v2, v59, v2
	v_add_u32_e32 v2, v60, v2
	v_add_u32_e32 v2, v61, v2
	v_add_u32_e32 v2, v62, v2
	v_add_u32_e32 v2, v63, v2
	v_add_u32_e32 v2, v64, v2
	v_add_u32_e32 v2, v65, v2
	v_add_u32_e32 v2, v66, v2
	v_cmp_ne_u32_e32 vcc, s10, v2
	s_cbranch_vccz .LBB0_89
	s_add_i32 s11, s11, 1
	s_and_b32 s4, s11, 0xff
	s_cmp_eq_u32 s4, 0
	s_cselect_b64 s[6:7], -1, 0
	s_and_b64 vcc, exec, s[6:7]
	s_sleep 1
	s_cbranch_vccnz .LBB0_96
	s_mov_b64 s[8:9], -1
	s_mov_b64 s[4:5], 0
	s_branch .LBB0_90
